# grid barrier poll loops: s_sleep 1 -> s_sleep 0 (tighter spin on the release flag)
# speedup vs baseline: 1.0015x; 1.0015x over previous
; __global__ void __launch_bounds__(256, 2) mega_kernel(Params p) {
;     ...
;   grid.sync();
.LBB0_77:
	s_sleep 0
	global_load_dword v2, v0, s[2:3] offset:32 sc1
	s_waitcnt vmcnt(0)
	v_and_b32_e32 v2, 0xffff0000, v2
	v_cmp_ne_u32_e32 vcc, v2, v1
	s_or_b64 s[6:7], vcc, s[6:7]
	s_andn2_b64 exec, exec, s[6:7]
	s_cbranch_execnz .LBB0_77

; DI void gbar(unsigned* bar, unsigned k) {
;     ...
;     while (__hip_atomic_load(bar + 64 * (9 + grp), __ATOMIC_RELAXED, __HIP_MEMORY_SCOPE_AGENT) < k) __builtin_amdgcn_s_sleep(1);
.LBB0_336:
	s_sleep 0
	global_load_dword v0, v1, s[96:97] offset:2304 sc1
	s_waitcnt vmcnt(0)
	v_cmp_gt_u32_e32 vcc, s66, v0
	s_cbranch_vccnz .LBB0_336

; DI void gbar(unsigned* bar, unsigned k) {
;     ...
;     while (__hip_atomic_load(bar + 64 * (9 + grp), __ATOMIC_RELAXED, __HIP_MEMORY_SCOPE_AGENT) < k) __builtin_amdgcn_s_sleep(1);
.LBB0_356:
	s_sleep 0
	global_load_dword v0, v1, s[96:97] offset:2304 sc1
	s_waitcnt vmcnt(0)
	v_cmp_gt_u32_e32 vcc, s1, v0
	s_cbranch_vccnz .LBB0_356

; DI void gbar(unsigned* bar, unsigned k) {
;     ...
;     while (__hip_atomic_load(bar + 64 * (9 + grp), __ATOMIC_RELAXED, __HIP_MEMORY_SCOPE_AGENT) < k) __builtin_amdgcn_s_sleep(1);
.LBB0_726:
	s_sleep 0
	global_load_dword v0, v1, s[96:97] offset:2304 sc1
	s_waitcnt vmcnt(0)
	v_cmp_gt_u32_e32 vcc, s64, v0
	s_cbranch_vccnz .LBB0_726

; DI void gbar(unsigned* bar, unsigned k) {
;     ...
;     while (__hip_atomic_load(bar + 64 * (9 + grp), __ATOMIC_RELAXED, __HIP_MEMORY_SCOPE_AGENT) < k) __builtin_amdgcn_s_sleep(1);
.LBB0_1054:
	s_sleep 0
	global_load_dword v0, v1, s[96:97] offset:2304 sc1
	s_waitcnt vmcnt(0)
	v_cmp_gt_u32_e32 vcc, s1, v0
	s_cbranch_vccnz .LBB0_1054
	s_getpc_b64 s[98:99]
